# v26: first K-iteration peeled with zero-C MFMAs in the FFN-up and w_in GEMMs (no accumulator zeroing)
# speedup vs baseline: 1.0019x; 1.0019x over previous
; #define PG8_STAGE(bufoff, gbase, voff) do { _Pragma("unroll") for (int _i = 0; _i < 2; ++_i) \
;         __builtin_amdgcn_global_load_lds((const unsigned*)((const char*)(gbase) + (voff)[_i]), (LAS unsigned*)(lds + (bufoff) + ldsw + _i * 8192), 16, 0, 0); } while (0)
; #define PG8_LDA(dst, b, h) do { _Pragma("unroll") for (int m = 0; m < 4; ++m) _Pragma("unroll") for (int k = 0; k < 2; ++k) dst[m][k] = *(const LAS f16x8*)(lds + PG8_SA(b, h) + aoff + m * 2048 + k * 1024); } while (0)
; #define PG8_LDB(dst, b, h) do { _Pragma("unroll") for (int n = 0; n < 2; ++n) _Pragma("unroll") for (int k = 0; k < 2; ++k) dst[n][k] = *(const LAS f16x8*)(lds + PG8_SB(b, h) + boff + n * 2048 + k * 1024); } while (0)
; #define PG8_MMA(ai, bj, At, Bt) do { __builtin_amdgcn_s_setprio(1); _Pragma("unroll") for (int m = 0; m < 4; ++m) _Pragma("unroll") for (int n = 0; n < 2; ++n) _Pragma("unroll") for (int k = 0; k < 2; ++k) \
;         acc[ai][bj][m][n] = mma16_<Epi::BF16>(Bt[n][k], At[m][k], acc[ai][bj][m][n]); __builtin_amdgcn_s_setprio(0); } while (0)
; #define PG8_WAIT_V(n) asm volatile("s_waitcnt vmcnt(" #n ")" ::: "memory")
; #define PG8_WAIT_L(n) asm volatile("s_waitcnt lgkmcnt(" #n ")" ::: "memory")
;     ...
;     for (;;) {
;         const bool has_next = S.next(ui + 1, nxt);
;         const char* nA = has_next ? (const char*)g.A + (size_t)nxt.pm * tA + (nxt.roff ? hA : (size_t)0) : cA; const char* nB = has_next ? (const char*)g.Bt + (size_t)nxt.pn * tB : cB;
;         for (int t = 0; t < nt; t += 2) {
;             const bool last = (t == nt - 2);
;             const char* a1 = cA + (size_t)(t + 1) * kstep;
;             const char* a2 = last ? nA : cA + (size_t)(t + 2) * kstep; const char* b2 = last ? nB : cB + (size_t)(t + 2) * kstep;
;             const char* a3 = a2 + kstep; const char* b3 = b2 + kstep;
;             if constexpr (SP2) {
;             PG8_LDB(B0, 0, 0); PG8_LDB(B1, 0, 1); PG8_SCHED; PG8_LDA(At, 0, 0); PG8_STAGE(PG8_SA(1, 1), a1 + hA, voffA);
;             PG8_WAIT_V(8); PG8_WAIT_L(0); PG8_BAR; PG8_MMA(0, 0, At, B0); PG8_MMA(0, 1, At, B1); PG8_BAR; PG8_SCHED;
;             PG8_LDA(At, 0, 1); PG8_STAGE(PG8_SB(0, 0), b2, voffB); PG8_STAGE(PG8_SB(0, 1), b2 + hB, voffB); PG8_STAGE(PG8_SA(0, 0), a2, voffA);
;             PG8_WAIT_V(8); PG8_WAIT_L(0); PG8_BAR; if (!cur.half) { PG8_MMA(1, 0, At, B0); PG8_MMA(1, 1, At, B1); } PG8_BAR; PG8_SCHED;
.LBB0_156:
	s_ashr_i32 s19, s18, 31
	s_lshl_b64 s[2:3], s[18:19], 19
	s_add_u32 s20, s13, s2
	s_addc_u32 s21, s14, s3
	s_and_b64 s[2:3], s[38:39], exec
	s_cselect_b32 s2, s21, s27
	s_cselect_b32 s3, s20, s26
	s_ashr_i32 s11, s10, 31
	s_lshl_b64 s[22:23], s[10:11], 19
	s_add_u32 s22, s1, s22
	s_addc_u32 s23, s12, s23
	s_and_b64 s[30:31], s[38:39], exec
	s_cselect_b32 s11, s23, s29
	s_cselect_b32 s19, s22, s28
	s_add_u32 s26, s26, 0x40080
	s_addc_u32 s27, s27, 0
	s_add_u32 s47, s28, 0x100
	s_addc_u32 s48, s29, 0
	s_mov_b32 s49, -2
	s_add_u32 s28, s26, 0xfffc0080
	s_addc_u32 s29, s27, -1
	s_add_i32 s50, 0, 0x10000
	s_cmp_eq_u32 s49, 12
	s_cselect_b32 s31, s2, s29
	s_cselect_b32 s30, s3, s28
	s_cselect_b32 s29, s11, s48
	s_cselect_b32 s28, s19, s47
	s_add_i32 s52, 0, 0x14000
	v_add_u32_e32 v156, s50, v141
	v_add_u32_e32 v172, s52, v141
	ds_read_b128 v[144:147], v156
	ds_read_b128 v[148:151], v156 offset:1024
	ds_read_b128 v[152:155], v156 offset:2048
	ds_read_b128 v[156:159], v156 offset:3072
	ds_read_b128 v[160:163], v172
	ds_read_b128 v[164:167], v172 offset:1024
	ds_read_b128 v[168:171], v172 offset:2048
	ds_read_b128 v[172:175], v172 offset:3072
	s_add_i32 m0, s25, 0xc000
	ds_read_b128 v[176:179], v143
	ds_read_b128 v[180:183], v143 offset:1024
	ds_read_b128 v[184:187], v143 offset:2048
	ds_read_b128 v[188:191], v143 offset:3072
	ds_read_b128 v[192:195], v143 offset:4096
	ds_read_b128 v[214:217], v143 offset:5120
	ds_read_b128 v[218:221], v143 offset:6144
	ds_read_b128 v[222:225], v143 offset:7168
	global_load_lds_dwordx4 v136, s[26:27]
	s_add_i32 m0, s25, 0xe000
	s_nop 0
	global_load_lds_dwordx4 v138, s[26:27]
	s_waitcnt vmcnt(8) lgkmcnt(0)
	s_barrier
	s_setprio 1
	v_mfma_f32_16x16x32_bf16 v[126:129], v[144:147], v[176:179], 0
	v_mfma_f32_16x16x32_bf16 v[118:121], v[152:155], v[176:179], 0
	v_mfma_f32_16x16x32_bf16 v[110:113], v[144:147], v[184:187], 0
	v_mfma_f32_16x16x32_bf16 v[102:105], v[152:155], v[184:187], 0
	v_mfma_f32_16x16x32_bf16 v[94:97], v[144:147], v[192:195], 0
	v_mfma_f32_16x16x32_bf16 v[86:89], v[152:155], v[192:195], 0
	v_mfma_f32_16x16x32_bf16 v[78:81], v[144:147], v[218:221], 0
	v_mfma_f32_16x16x32_bf16 v[70:73], v[152:155], v[218:221], 0
	v_mfma_f32_16x16x32_bf16 v[126:129], v[148:151], v[180:183], v[126:129]
	v_mfma_f32_16x16x32_bf16 v[118:121], v[156:159], v[180:183], v[118:121]
	v_mfma_f32_16x16x32_bf16 v[110:113], v[148:151], v[188:191], v[110:113]
	v_mfma_f32_16x16x32_bf16 v[102:105], v[156:159], v[188:191], v[102:105]
	v_mfma_f32_16x16x32_bf16 v[94:97], v[148:151], v[214:217], v[94:97]
	v_mfma_f32_16x16x32_bf16 v[86:89], v[156:159], v[214:217], v[86:89]
	v_mfma_f32_16x16x32_bf16 v[78:81], v[148:151], v[222:225], v[78:81]
	v_mfma_f32_16x16x32_bf16 v[70:73], v[156:159], v[222:225], v[70:73]
	s_setprio 0
	s_setprio 1
	v_mfma_f32_16x16x32_bf16 v[122:125], v[160:163], v[176:179], 0
	v_mfma_f32_16x16x32_bf16 v[114:117], v[168:171], v[176:179], 0
	v_mfma_f32_16x16x32_bf16 v[106:109], v[160:163], v[184:187], 0
	v_mfma_f32_16x16x32_bf16 v[98:101], v[168:171], v[184:187], 0
	v_mfma_f32_16x16x32_bf16 v[90:93], v[160:163], v[192:195], 0
	v_mfma_f32_16x16x32_bf16 v[82:85], v[168:171], v[192:195], 0
	v_mfma_f32_16x16x32_bf16 v[74:77], v[160:163], v[218:221], 0
	v_mfma_f32_16x16x32_bf16 v[66:69], v[168:171], v[218:221], 0
	v_mfma_f32_16x16x32_bf16 v[122:125], v[164:167], v[180:183], v[122:125]
	v_mfma_f32_16x16x32_bf16 v[114:117], v[172:175], v[180:183], v[114:117]
	v_mfma_f32_16x16x32_bf16 v[106:109], v[164:167], v[188:191], v[106:109]
	v_mfma_f32_16x16x32_bf16 v[98:101], v[172:175], v[188:191], v[98:101]
	v_mfma_f32_16x16x32_bf16 v[90:93], v[164:167], v[214:217], v[90:93]
	v_mfma_f32_16x16x32_bf16 v[82:85], v[172:175], v[214:217], v[82:85]
	v_mfma_f32_16x16x32_bf16 v[74:77], v[164:167], v[222:225], v[74:77]
	v_mfma_f32_16x16x32_bf16 v[66:69], v[172:175], v[222:225], v[66:69]
	s_setprio 0
	s_barrier
	s_add_i32 s50, s50, s34
	s_mov_b32 m0, s50
	ds_read_b128 v[176:179], v143 offset:16384
	ds_read_b128 v[180:183], v143 offset:17408
	ds_read_b128 v[184:187], v143 offset:18432
	ds_read_b128 v[188:191], v143 offset:19456
	ds_read_b128 v[192:195], v143 offset:20480
	ds_read_b128 v[214:217], v143 offset:21504
	ds_read_b128 v[218:221], v143 offset:22528
	ds_read_b128 v[222:225], v143 offset:23552
	global_load_lds_dwordx4 v0, s[28:29]
	s_add_i32 m0, s50, 0x2000
	s_add_u32 s50, s28, 0x40000
	s_addc_u32 s51, s29, 0
	s_add_i32 s52, s52, s34
	global_load_lds_dwordx4 v130, s[28:29]
	s_mov_b32 m0, s52
	s_nop 0
	global_load_lds_dwordx4 v0, s[50:51]
	s_add_i32 m0, s52, 0x2000
	s_nop 0
	global_load_lds_dwordx4 v130, s[50:51]
	s_mov_b32 m0, s25
	s_nop 0
	global_load_lds_dwordx4 v134, s[30:31]
	s_mov_b32 m0, s36
	s_nop 0
	global_load_lds_dwordx4 v132, s[30:31]
	s_waitcnt vmcnt(8) lgkmcnt(0)
	s_barrier
; #define PG8_STAGE(bufoff, gbase, voff) do { _Pragma("unroll") for (int _i = 0; _i < 2; ++_i) \
;         __builtin_amdgcn_global_load_lds((const unsigned*)((const char*)(gbase) + (voff)[_i]), (LAS unsigned*)(lds + (bufoff) + ldsw + _i * 8192), 16, 0, 0); } while (0)
; #define PG8_LDA(dst, b, h) do { _Pragma("unroll") for (int m = 0; m < 4; ++m) _Pragma("unroll") for (int k = 0; k < 2; ++k) dst[m][k] = *(const LAS f16x8*)(lds + PG8_SA(b, h) + aoff + m * 2048 + k * 1024); } while (0)
; #define PG8_LDB(dst, b, h) do { _Pragma("unroll") for (int n = 0; n < 2; ++n) _Pragma("unroll") for (int k = 0; k < 2; ++k) dst[n][k] = *(const LAS f16x8*)(lds + PG8_SB(b, h) + boff + n * 2048 + k * 1024); } while (0)
; #define PG8_MMA(ai, bj, At, Bt) do { __builtin_amdgcn_s_setprio(1); _Pragma("unroll") for (int m = 0; m < 4; ++m) _Pragma("unroll") for (int n = 0; n < 2; ++n) _Pragma("unroll") for (int k = 0; k < 2; ++k) \
;         acc[ai][bj][m][n] = mma16_<Epi::BF16>(Bt[n][k], At[m][k], acc[ai][bj][m][n]); __builtin_amdgcn_s_setprio(0); } while (0)
; #define PG8_WAIT_V(n) asm volatile("s_waitcnt vmcnt(" #n ")" ::: "memory")
; #define PG8_WAIT_L(n) asm volatile("s_waitcnt lgkmcnt(" #n ")" ::: "memory")
; #define PG8_BAR __builtin_amdgcn_s_barrier()
; #define PG8_SCHED __builtin_amdgcn_sched_barrier(0)
;     ...
;             PG8_WAIT_V(8); PG8_WAIT_L(0); PG8_BAR; if (!cur.half) { PG8_MMA(1, 0, At, B0); PG8_MMA(1, 1, At, B1); } PG8_BAR; PG8_SCHED;
;             PG8_LDB(B0, 1, 0); PG8_LDB(B1, 1, 1); PG8_SCHED; PG8_LDA(At, 1, 0); PG8_STAGE(PG8_SA(0, 1), a2 + hA, voffA);
;             PG8_WAIT_V(8); PG8_WAIT_L(0); PG8_BAR; PG8_MMA(0, 0, At, B0); PG8_MMA(0, 1, At, B1); PG8_BAR; PG8_SCHED;
;             PG8_LDA(At, 1, 1); PG8_STAGE(PG8_SB(1, 0), b3, voffB); PG8_STAGE(PG8_SB(1, 1), b3 + hB, voffB); PG8_STAGE(PG8_SA(1, 0), a3, voffA);
;             PG8_WAIT_V(8); PG8_WAIT_L(0); PG8_BAR; if (!cur.half) { PG8_MMA(1, 0, At, B0); PG8_MMA(1, 1, At, B1); } PG8_BAR; PG8_SCHED;
	s_setprio 1
	v_mfma_f32_16x16x32_bf16 v[62:65], v[144:147], v[176:179], 0
	v_mfma_f32_16x16x32_bf16 v[54:57], v[152:155], v[176:179], 0
	v_mfma_f32_16x16x32_bf16 v[46:49], v[144:147], v[184:187], 0
	v_mfma_f32_16x16x32_bf16 v[38:41], v[152:155], v[184:187], 0
	v_mfma_f32_16x16x32_bf16 v[30:33], v[144:147], v[192:195], 0
	v_mfma_f32_16x16x32_bf16 v[22:25], v[152:155], v[192:195], 0
	v_mfma_f32_16x16x32_bf16 v[14:17], v[144:147], v[218:221], 0
	v_mfma_f32_16x16x32_bf16 v[6:9], v[152:155], v[218:221], 0
	v_mfma_f32_16x16x32_bf16 v[62:65], v[148:151], v[180:183], v[62:65]
	v_mfma_f32_16x16x32_bf16 v[54:57], v[156:159], v[180:183], v[54:57]
	v_mfma_f32_16x16x32_bf16 v[46:49], v[148:151], v[188:191], v[46:49]
	v_mfma_f32_16x16x32_bf16 v[38:41], v[156:159], v[188:191], v[38:41]
	v_mfma_f32_16x16x32_bf16 v[30:33], v[148:151], v[214:217], v[30:33]
	v_mfma_f32_16x16x32_bf16 v[22:25], v[156:159], v[214:217], v[22:25]
	v_mfma_f32_16x16x32_bf16 v[14:17], v[148:151], v[222:225], v[14:17]
	v_mfma_f32_16x16x32_bf16 v[6:9], v[156:159], v[222:225], v[6:9]
	s_setprio 0
	s_setprio 1
	v_mfma_f32_16x16x32_bf16 v[58:61], v[160:163], v[176:179], 0
	v_mfma_f32_16x16x32_bf16 v[50:53], v[168:171], v[176:179], 0
	v_mfma_f32_16x16x32_bf16 v[42:45], v[160:163], v[184:187], 0
	v_mfma_f32_16x16x32_bf16 v[34:37], v[168:171], v[184:187], 0
	v_mfma_f32_16x16x32_bf16 v[26:29], v[160:163], v[192:195], 0
	v_mfma_f32_16x16x32_bf16 v[18:21], v[168:171], v[192:195], 0
	v_mfma_f32_16x16x32_bf16 v[10:13], v[160:163], v[218:221], 0
	v_mfma_f32_16x16x32_bf16 v[2:5], v[168:171], v[218:221], 0
	v_mfma_f32_16x16x32_bf16 v[58:61], v[164:167], v[180:183], v[58:61]
	v_mfma_f32_16x16x32_bf16 v[50:53], v[172:175], v[180:183], v[50:53]
	v_mfma_f32_16x16x32_bf16 v[42:45], v[164:167], v[188:191], v[42:45]
	v_mfma_f32_16x16x32_bf16 v[34:37], v[172:175], v[188:191], v[34:37]
	v_mfma_f32_16x16x32_bf16 v[26:29], v[164:167], v[214:217], v[26:29]
	v_mfma_f32_16x16x32_bf16 v[18:21], v[172:175], v[214:217], v[18:21]
	v_mfma_f32_16x16x32_bf16 v[10:13], v[164:167], v[222:225], v[10:13]
	v_mfma_f32_16x16x32_bf16 v[2:5], v[172:175], v[222:225], v[2:5]
	s_setprio 0
	s_barrier
	s_add_i32 s50, 0, 0x18000
	s_add_i32 s51, 0, 0x1c000
	v_add_u32_e32 v156, s50, v141
	v_add_u32_e32 v172, s51, v141
	ds_read_b128 v[144:147], v156
	ds_read_b128 v[148:151], v156 offset:1024
	ds_read_b128 v[152:155], v156 offset:2048
	ds_read_b128 v[156:159], v156 offset:3072
	ds_read_b128 v[160:163], v172
	ds_read_b128 v[164:167], v172 offset:1024
	ds_read_b128 v[168:171], v172 offset:2048
	ds_read_b128 v[172:175], v172 offset:3072
	s_add_u32 s30, s30, 0x40000
	s_addc_u32 s31, s31, 0
	s_add_u32 s98, s30, 0xfffc0080
	s_addc_u32 s99, s31, -1
	s_mov_b32 m0, s37
	ds_read_b128 v[176:179], v143 offset:32768
	ds_read_b128 v[180:183], v143 offset:33792
	ds_read_b128 v[184:187], v143 offset:34816
	ds_read_b128 v[188:191], v143 offset:35840
	ds_read_b128 v[192:195], v143 offset:36864
	ds_read_b128 v[214:217], v143 offset:37888
	ds_read_b128 v[218:221], v143 offset:38912
	ds_read_b128 v[222:225], v143 offset:39936
	global_load_lds_dwordx4 v134, s[30:31]
	s_mov_b32 m0, s40
	s_nop 0
	global_load_lds_dwordx4 v132, s[30:31]
	s_waitcnt vmcnt(8) lgkmcnt(0)
	s_barrier
	s_setprio 1
	v_mfma_f32_16x16x32_bf16 v[126:129], v[144:147], v[176:179], v[126:129]
	v_mfma_f32_16x16x32_bf16 v[118:121], v[152:155], v[176:179], v[118:121]
	v_mfma_f32_16x16x32_bf16 v[110:113], v[144:147], v[184:187], v[110:113]
	v_mfma_f32_16x16x32_bf16 v[102:105], v[152:155], v[184:187], v[102:105]
	v_mfma_f32_16x16x32_bf16 v[94:97], v[144:147], v[192:195], v[94:97]
	v_mfma_f32_16x16x32_bf16 v[86:89], v[152:155], v[192:195], v[86:89]
	v_mfma_f32_16x16x32_bf16 v[78:81], v[144:147], v[218:221], v[78:81]
	v_mfma_f32_16x16x32_bf16 v[70:73], v[152:155], v[218:221], v[70:73]
	v_mfma_f32_16x16x32_bf16 v[126:129], v[148:151], v[180:183], v[126:129]
	v_mfma_f32_16x16x32_bf16 v[118:121], v[156:159], v[180:183], v[118:121]
	v_mfma_f32_16x16x32_bf16 v[110:113], v[148:151], v[188:191], v[110:113]
	v_mfma_f32_16x16x32_bf16 v[102:105], v[156:159], v[188:191], v[102:105]
	v_mfma_f32_16x16x32_bf16 v[94:97], v[148:151], v[214:217], v[94:97]
	v_mfma_f32_16x16x32_bf16 v[86:89], v[156:159], v[214:217], v[86:89]
	v_mfma_f32_16x16x32_bf16 v[78:81], v[148:151], v[222:225], v[78:81]
	v_mfma_f32_16x16x32_bf16 v[70:73], v[156:159], v[222:225], v[70:73]
	s_setprio 0
	s_setprio 1
	v_mfma_f32_16x16x32_bf16 v[122:125], v[160:163], v[176:179], v[122:125]
	v_mfma_f32_16x16x32_bf16 v[114:117], v[168:171], v[176:179], v[114:117]
	v_mfma_f32_16x16x32_bf16 v[106:109], v[160:163], v[184:187], v[106:109]
	v_mfma_f32_16x16x32_bf16 v[98:101], v[168:171], v[184:187], v[98:101]
	v_mfma_f32_16x16x32_bf16 v[90:93], v[160:163], v[192:195], v[90:93]
	v_mfma_f32_16x16x32_bf16 v[82:85], v[168:171], v[192:195], v[82:85]
	v_mfma_f32_16x16x32_bf16 v[74:77], v[160:163], v[218:221], v[74:77]
	v_mfma_f32_16x16x32_bf16 v[66:69], v[168:171], v[218:221], v[66:69]
	v_mfma_f32_16x16x32_bf16 v[122:125], v[164:167], v[180:183], v[122:125]
	v_mfma_f32_16x16x32_bf16 v[114:117], v[172:175], v[180:183], v[114:117]
	v_mfma_f32_16x16x32_bf16 v[106:109], v[164:167], v[188:191], v[106:109]
	v_mfma_f32_16x16x32_bf16 v[98:101], v[172:175], v[188:191], v[98:101]
	v_mfma_f32_16x16x32_bf16 v[90:93], v[164:167], v[214:217], v[90:93]
	v_mfma_f32_16x16x32_bf16 v[82:85], v[172:175], v[214:217], v[82:85]
	v_mfma_f32_16x16x32_bf16 v[74:77], v[164:167], v[222:225], v[74:77]
	v_mfma_f32_16x16x32_bf16 v[66:69], v[172:175], v[222:225], v[66:69]
	s_setprio 0
	s_barrier
; #define PG8_STAGE(bufoff, gbase, voff) do { _Pragma("unroll") for (int _i = 0; _i < 2; ++_i) \
;         __builtin_amdgcn_global_load_lds((const unsigned*)((const char*)(gbase) + (voff)[_i]), (LAS unsigned*)(lds + (bufoff) + ldsw + _i * 8192), 16, 0, 0); } while (0)
; #define PG8_LDA(dst, b, h) do { _Pragma("unroll") for (int m = 0; m < 4; ++m) _Pragma("unroll") for (int k = 0; k < 2; ++k) dst[m][k] = *(const LAS f16x8*)(lds + PG8_SA(b, h) + aoff + m * 2048 + k * 1024); } while (0)
; #define PG8_LDB(dst, b, h) do { _Pragma("unroll") for (int n = 0; n < 2; ++n) _Pragma("unroll") for (int k = 0; k < 2; ++k) dst[n][k] = *(const LAS f16x8*)(lds + PG8_SB(b, h) + boff + n * 2048 + k * 1024); } while (0)
; #define PG8_WAIT_V(n) asm volatile("s_waitcnt vmcnt(" #n ")" ::: "memory")
; #define PG8_WAIT_L(n) asm volatile("s_waitcnt lgkmcnt(" #n ")" ::: "memory")
; #define PG8_BAR __builtin_amdgcn_s_barrier()
;     ...
;         for (int t = 0; t < nt; t += 2) {
;             const bool last = (t == nt - 2);
;             const char* a1 = cA + (size_t)(t + 1) * kstep;
;             const char* a2 = last ? nA : cA + (size_t)(t + 2) * kstep; const char* b2 = last ? nB : cB + (size_t)(t + 2) * kstep;
;             const char* a3 = a2 + kstep; const char* b3 = b2 + kstep;
;             if constexpr (SP2) {
;             PG8_LDB(B0, 0, 0); PG8_LDB(B1, 0, 1); PG8_SCHED; PG8_LDA(At, 0, 0); PG8_STAGE(PG8_SA(1, 1), a1 + hA, voffA);
;             PG8_WAIT_V(8); PG8_WAIT_L(0); PG8_BAR; PG8_MMA(0, 0, At, B0); PG8_MMA(0, 1, At, B1); PG8_BAR; PG8_SCHED;
;             PG8_LDA(At, 0, 1); PG8_STAGE(PG8_SB(0, 0), b2, voffB); PG8_STAGE(PG8_SB(0, 1), b2 + hB, voffB); PG8_STAGE(PG8_SA(0, 0), a2, voffA);
;             PG8_WAIT_V(8); PG8_WAIT_L(0); PG8_BAR; if (!cur.half) { PG8_MMA(1, 0, At, B0); PG8_MMA(1, 1, At, B1); } PG8_BAR; PG8_SCHED;
;             PG8_LDB(B0, 1, 0); PG8_LDB(B1, 1, 1); PG8_SCHED; PG8_LDA(At, 1, 0); PG8_STAGE(PG8_SA(0, 1), a2 + hA, voffA);
;             PG8_WAIT_V(8); PG8_WAIT_L(0); PG8_BAR; PG8_MMA(0, 0, At, B0); PG8_MMA(0, 1, At, B1); PG8_BAR; PG8_SCHED;
;             PG8_LDA(At, 1, 1); PG8_STAGE(PG8_SB(1, 0), b3, voffB); PG8_STAGE(PG8_SB(1, 1), b3 + hB, voffB); PG8_STAGE(PG8_SA(1, 0), a3, voffA);
;             PG8_WAIT_V(8); PG8_WAIT_L(0); PG8_BAR; if (!cur.half) { PG8_MMA(1, 0, At, B0); PG8_MMA(1, 1, At, B1); } PG8_BAR; PG8_SCHED;
	s_add_i32 s30, s50, s34
	s_add_u32 s28, s28, 0x80
	s_addc_u32 s29, s29, 0
	s_mov_b32 m0, s30
	ds_read_b128 v[176:179], v143 offset:49152
	ds_read_b128 v[180:183], v143 offset:50176
	ds_read_b128 v[184:187], v143 offset:51200
	ds_read_b128 v[188:191], v143 offset:52224
	ds_read_b128 v[192:195], v143 offset:53248
	ds_read_b128 v[214:217], v143 offset:54272
	ds_read_b128 v[218:221], v143 offset:55296
	ds_read_b128 v[222:225], v143 offset:56320
	global_load_lds_dwordx4 v0, s[28:29]
	s_add_i32 m0, s30, 0x2000
	s_add_i32 s30, s51, s34
	global_load_lds_dwordx4 v130, s[28:29]
	s_add_u32 s28, s28, 0x40000
	s_addc_u32 s29, s29, 0
	s_mov_b32 m0, s30
	s_nop 0
	global_load_lds_dwordx4 v0, s[28:29]
	s_add_i32 m0, s30, 0x2000
	s_nop 0
	global_load_lds_dwordx4 v130, s[28:29]
	s_mov_b32 m0, s41
	s_nop 0
	global_load_lds_dwordx4 v134, s[98:99]
	s_mov_b32 m0, s42
	s_nop 0
	global_load_lds_dwordx4 v132, s[98:99]
	s_waitcnt vmcnt(8) lgkmcnt(0)
	s_barrier
	s_setprio 1
	v_mfma_f32_16x16x32_bf16 v[62:65], v[144:147], v[176:179], v[62:65]
	v_mfma_f32_16x16x32_bf16 v[54:57], v[152:155], v[176:179], v[54:57]
	v_mfma_f32_16x16x32_bf16 v[46:49], v[144:147], v[184:187], v[46:49]
	v_mfma_f32_16x16x32_bf16 v[38:41], v[152:155], v[184:187], v[38:41]
	v_mfma_f32_16x16x32_bf16 v[30:33], v[144:147], v[192:195], v[30:33]
	v_mfma_f32_16x16x32_bf16 v[22:25], v[152:155], v[192:195], v[22:25]
	v_mfma_f32_16x16x32_bf16 v[14:17], v[144:147], v[218:221], v[14:17]
	v_mfma_f32_16x16x32_bf16 v[6:9], v[152:155], v[218:221], v[6:9]
	v_mfma_f32_16x16x32_bf16 v[62:65], v[148:151], v[180:183], v[62:65]
	v_mfma_f32_16x16x32_bf16 v[54:57], v[156:159], v[180:183], v[54:57]
	v_mfma_f32_16x16x32_bf16 v[46:49], v[148:151], v[188:191], v[46:49]
	v_mfma_f32_16x16x32_bf16 v[38:41], v[156:159], v[188:191], v[38:41]
	v_mfma_f32_16x16x32_bf16 v[30:33], v[148:151], v[214:217], v[30:33]
	v_mfma_f32_16x16x32_bf16 v[22:25], v[156:159], v[214:217], v[22:25]
	v_mfma_f32_16x16x32_bf16 v[14:17], v[148:151], v[222:225], v[14:17]
	v_mfma_f32_16x16x32_bf16 v[6:9], v[156:159], v[222:225], v[6:9]
	s_setprio 0
	s_setprio 1
	v_mfma_f32_16x16x32_bf16 v[58:61], v[160:163], v[176:179], v[58:61]
	v_mfma_f32_16x16x32_bf16 v[50:53], v[168:171], v[176:179], v[50:53]
	v_mfma_f32_16x16x32_bf16 v[42:45], v[160:163], v[184:187], v[42:45]
	v_mfma_f32_16x16x32_bf16 v[34:37], v[168:171], v[184:187], v[34:37]
	v_mfma_f32_16x16x32_bf16 v[26:29], v[160:163], v[192:195], v[26:29]
	v_mfma_f32_16x16x32_bf16 v[18:21], v[168:171], v[192:195], v[18:21]
	v_mfma_f32_16x16x32_bf16 v[10:13], v[160:163], v[218:221], v[10:13]
	v_mfma_f32_16x16x32_bf16 v[2:5], v[168:171], v[218:221], v[2:5]
	v_mfma_f32_16x16x32_bf16 v[58:61], v[164:167], v[180:183], v[58:61]
	v_mfma_f32_16x16x32_bf16 v[50:53], v[172:175], v[180:183], v[50:53]
	v_mfma_f32_16x16x32_bf16 v[42:45], v[164:167], v[188:191], v[42:45]
	v_mfma_f32_16x16x32_bf16 v[34:37], v[172:175], v[188:191], v[34:37]
	v_mfma_f32_16x16x32_bf16 v[26:29], v[164:167], v[214:217], v[26:29]
	v_mfma_f32_16x16x32_bf16 v[18:21], v[172:175], v[214:217], v[18:21]
	v_mfma_f32_16x16x32_bf16 v[10:13], v[164:167], v[222:225], v[10:13]
	v_mfma_f32_16x16x32_bf16 v[2:5], v[172:175], v[222:225], v[2:5]
	s_setprio 0
	s_barrier
	s_add_i32 s49, s49, 2
	s_add_u32 s26, s26, 0x100
	s_addc_u32 s27, s27, 0
	s_add_u32 s47, s47, 0x100
	s_addc_u32 s48, s48, 0
	s_cmp_gt_u32 s49, 13

; #define PG8_STAGE(bufoff, gbase, voff) do { _Pragma("unroll") for (int _i = 0; _i < 2; ++_i) \
;         __builtin_amdgcn_global_load_lds((const unsigned*)((const char*)(gbase) + (voff)[_i]), (LAS unsigned*)(lds + (bufoff) + ldsw + _i * 8192), 16, 0, 0); } while (0)
; #define PG8_LDA(dst, b, h) do { _Pragma("unroll") for (int m = 0; m < 4; ++m) _Pragma("unroll") for (int k = 0; k < 2; ++k) dst[m][k] = *(const LAS f16x8*)(lds + PG8_SA(b, h) + aoff + m * 2048 + k * 1024); } while (0)
; #define PG8_LDB(dst, b, h) do { _Pragma("unroll") for (int n = 0; n < 2; ++n) _Pragma("unroll") for (int k = 0; k < 2; ++k) dst[n][k] = *(const LAS f16x8*)(lds + PG8_SB(b, h) + boff + n * 2048 + k * 1024); } while (0)
; #define PG8_MMA(ai, bj, At, Bt) do { __builtin_amdgcn_s_setprio(1); _Pragma("unroll") for (int m = 0; m < 4; ++m) _Pragma("unroll") for (int n = 0; n < 2; ++n) _Pragma("unroll") for (int k = 0; k < 2; ++k) \
;         acc[ai][bj][m][n] = mma16_<Epi::BF16>(Bt[n][k], At[m][k], acc[ai][bj][m][n]); __builtin_amdgcn_s_setprio(0); } while (0)
; #define PG8_WAIT_V(n) asm volatile("s_waitcnt vmcnt(" #n ")" ::: "memory")
; #define PG8_WAIT_L(n) asm volatile("s_waitcnt lgkmcnt(" #n ")" ::: "memory")
;     ...
;     for (;;) {
;         const bool has_next = S.next(ui + 1, nxt);
;         const char* nA = has_next ? (const char*)g.A + (size_t)nxt.pm * tA + (nxt.roff ? hA : (size_t)0) : cA; const char* nB = has_next ? (const char*)g.Bt + (size_t)nxt.pn * tB : cB;
;         for (int t = 0; t < nt; t += 2) {
;             const bool last = (t == nt - 2);
;             const char* a1 = cA + (size_t)(t + 1) * kstep;
;             const char* a2 = last ? nA : cA + (size_t)(t + 2) * kstep; const char* b2 = last ? nB : cB + (size_t)(t + 2) * kstep;
;             const char* a3 = a2 + kstep; const char* b3 = b2 + kstep;
;             if constexpr (SP2) {
;             PG8_LDB(B0, 0, 0); PG8_LDB(B1, 0, 1); PG8_SCHED; PG8_LDA(At, 0, 0); PG8_STAGE(PG8_SA(1, 1), a1 + hA, voffA);
;             PG8_WAIT_V(8); PG8_WAIT_L(0); PG8_BAR; PG8_MMA(0, 0, At, B0); PG8_MMA(0, 1, At, B1); PG8_BAR; PG8_SCHED;
;             PG8_LDA(At, 0, 1); PG8_STAGE(PG8_SB(0, 0), b2, voffB); PG8_STAGE(PG8_SB(0, 1), b2 + hB, voffB); PG8_STAGE(PG8_SA(0, 0), a2, voffA);
;             PG8_WAIT_V(8); PG8_WAIT_L(0); PG8_BAR; if (!cur.half) { PG8_MMA(1, 0, At, B0); PG8_MMA(1, 1, At, B1); } PG8_BAR; PG8_SCHED;
.LBB0_515:
	s_ashr_i32 s21, s20, 31
	s_lshl_b64 s[2:3], s[20:21], 19
	s_add_u32 s22, s13, s2
	s_addc_u32 s23, s14, s3
	s_and_b64 s[2:3], s[38:39], exec
	s_cselect_b32 s2, s23, s27
	s_cselect_b32 s3, s22, s26
	s_ashr_i32 s19, s18, 31
	s_lshl_b64 s[24:25], s[18:19], 19
	s_add_u32 s24, s1, s24
	s_addc_u32 s25, s12, s25
	s_and_b64 s[30:31], s[38:39], exec
	s_cselect_b32 s19, s25, s29
	s_cselect_b32 s21, s24, s28
	s_add_u32 s26, s26, 0x40080
	s_addc_u32 s27, s27, 0
	s_add_u32 s47, s28, 0x100
	s_addc_u32 s48, s29, 0
	s_mov_b32 s49, -2
	s_add_u32 s28, s26, 0xfffc0080
	s_addc_u32 s29, s27, -1
	s_add_i32 s50, 0, 0x10000
	s_cmp_eq_u32 s49, 12
	s_cselect_b32 s31, s2, s29
	s_cselect_b32 s30, s3, s28
	v_add_u32_e32 v142, s50, v145
	s_cselect_b32 s29, s19, s48
	s_cselect_b32 s28, s21, s47
	s_add_i32 s52, 0, 0x14000
	ds_read_b128 v[148:151], v142
	ds_read_b128 v[152:155], v142 offset:1024
	ds_read_b128 v[156:159], v142 offset:2048
	ds_read_b128 v[160:163], v142 offset:3072
	v_add_u32_e32 v142, s52, v145
	ds_read_b128 v[164:167], v142
	ds_read_b128 v[168:171], v142 offset:1024
	ds_read_b128 v[172:175], v142 offset:2048
	ds_read_b128 v[176:179], v142 offset:3072
	s_add_i32 m0, s17, 0xc000
	ds_read_b128 v[180:183], v147
	ds_read_b128 v[184:187], v147 offset:1024
	ds_read_b128 v[188:191], v147 offset:2048
	ds_read_b128 v[192:195], v147 offset:3072
	ds_read_b128 v[214:217], v147 offset:4096
	ds_read_b128 v[218:221], v147 offset:5120
	ds_read_b128 v[222:225], v147 offset:6144
	ds_read_b128 v[226:229], v147 offset:7168
	global_load_lds_dwordx4 v138, s[26:27]
	s_add_i32 m0, s17, 0xe000
	s_nop 0
	global_load_lds_dwordx4 v140, s[26:27]
	s_waitcnt vmcnt(8) lgkmcnt(0)
	s_barrier
	s_setprio 1
	v_mfma_f32_16x16x32_bf16 v[126:129], v[148:151], v[180:183], 0
	v_mfma_f32_16x16x32_bf16 v[122:125], v[156:159], v[180:183], 0
	v_mfma_f32_16x16x32_bf16 v[118:121], v[148:151], v[188:191], 0
	v_mfma_f32_16x16x32_bf16 v[114:117], v[156:159], v[188:191], 0
	v_mfma_f32_16x16x32_bf16 v[102:105], v[148:151], v[214:217], 0
	v_mfma_f32_16x16x32_bf16 v[98:101], v[156:159], v[214:217], 0
	v_mfma_f32_16x16x32_bf16 v[86:89], v[148:151], v[222:225], 0
	v_mfma_f32_16x16x32_bf16 v[82:85], v[156:159], v[222:225], 0
	v_mfma_f32_16x16x32_bf16 v[126:129], v[152:155], v[184:187], v[126:129]
	v_mfma_f32_16x16x32_bf16 v[122:125], v[160:163], v[184:187], v[122:125]
	v_mfma_f32_16x16x32_bf16 v[118:121], v[152:155], v[192:195], v[118:121]
	v_mfma_f32_16x16x32_bf16 v[114:117], v[160:163], v[192:195], v[114:117]
	v_mfma_f32_16x16x32_bf16 v[102:105], v[152:155], v[218:221], v[102:105]
	v_mfma_f32_16x16x32_bf16 v[98:101], v[160:163], v[218:221], v[98:101]
	v_mfma_f32_16x16x32_bf16 v[86:89], v[152:155], v[226:229], v[86:89]
	v_mfma_f32_16x16x32_bf16 v[82:85], v[160:163], v[226:229], v[82:85]
	s_setprio 0
	s_setprio 1
	v_mfma_f32_16x16x32_bf16 v[110:113], v[164:167], v[180:183], 0
	v_mfma_f32_16x16x32_bf16 v[106:109], v[172:175], v[180:183], 0
	v_mfma_f32_16x16x32_bf16 v[94:97], v[164:167], v[188:191], 0
	v_mfma_f32_16x16x32_bf16 v[90:93], v[172:175], v[188:191], 0
	v_mfma_f32_16x16x32_bf16 v[78:81], v[164:167], v[214:217], 0
	v_mfma_f32_16x16x32_bf16 v[74:77], v[172:175], v[214:217], 0
	v_mfma_f32_16x16x32_bf16 v[70:73], v[164:167], v[222:225], 0
	v_mfma_f32_16x16x32_bf16 v[66:69], v[172:175], v[222:225], 0
	v_mfma_f32_16x16x32_bf16 v[110:113], v[168:171], v[184:187], v[110:113]
	v_mfma_f32_16x16x32_bf16 v[106:109], v[176:179], v[184:187], v[106:109]
	v_mfma_f32_16x16x32_bf16 v[94:97], v[168:171], v[192:195], v[94:97]
	v_mfma_f32_16x16x32_bf16 v[90:93], v[176:179], v[192:195], v[90:93]
	v_mfma_f32_16x16x32_bf16 v[78:81], v[168:171], v[218:221], v[78:81]
	v_mfma_f32_16x16x32_bf16 v[74:77], v[176:179], v[218:221], v[74:77]
	v_mfma_f32_16x16x32_bf16 v[70:73], v[168:171], v[226:229], v[70:73]
	v_mfma_f32_16x16x32_bf16 v[66:69], v[176:179], v[226:229], v[66:69]
	s_setprio 0
	s_barrier
	s_add_i32 s50, s50, s34
	s_mov_b32 m0, s50
	ds_read_b128 v[180:183], v147 offset:16384
	ds_read_b128 v[184:187], v147 offset:17408
	ds_read_b128 v[188:191], v147 offset:18432
	ds_read_b128 v[192:195], v147 offset:19456
	ds_read_b128 v[214:217], v147 offset:20480
	ds_read_b128 v[218:221], v147 offset:21504
	ds_read_b128 v[222:225], v147 offset:22528
	ds_read_b128 v[226:229], v147 offset:23552
	global_load_lds_dwordx4 v0, s[28:29]
	s_add_i32 m0, s50, 0x2000
	s_add_u32 s50, s28, 0x40000
	s_addc_u32 s51, s29, 0
	s_add_i32 s52, s52, s34
	global_load_lds_dwordx4 v130, s[28:29]
	s_mov_b32 m0, s52
	s_nop 0
	global_load_lds_dwordx4 v0, s[50:51]
	s_add_i32 m0, s52, 0x2000
	s_nop 0
	global_load_lds_dwordx4 v130, s[50:51]
	s_mov_b32 m0, s17
	s_nop 0
	global_load_lds_dwordx4 v134, s[30:31]
	s_mov_b32 m0, s36
	s_nop 0
	global_load_lds_dwordx4 v132, s[30:31]
	s_waitcnt vmcnt(8) lgkmcnt(0)
	s_barrier
; #define PG8_STAGE(bufoff, gbase, voff) do { _Pragma("unroll") for (int _i = 0; _i < 2; ++_i) \
;         __builtin_amdgcn_global_load_lds((const unsigned*)((const char*)(gbase) + (voff)[_i]), (LAS unsigned*)(lds + (bufoff) + ldsw + _i * 8192), 16, 0, 0); } while (0)
; #define PG8_LDA(dst, b, h) do { _Pragma("unroll") for (int m = 0; m < 4; ++m) _Pragma("unroll") for (int k = 0; k < 2; ++k) dst[m][k] = *(const LAS f16x8*)(lds + PG8_SA(b, h) + aoff + m * 2048 + k * 1024); } while (0)
; #define PG8_LDB(dst, b, h) do { _Pragma("unroll") for (int n = 0; n < 2; ++n) _Pragma("unroll") for (int k = 0; k < 2; ++k) dst[n][k] = *(const LAS f16x8*)(lds + PG8_SB(b, h) + boff + n * 2048 + k * 1024); } while (0)
; #define PG8_MMA(ai, bj, At, Bt) do { __builtin_amdgcn_s_setprio(1); _Pragma("unroll") for (int m = 0; m < 4; ++m) _Pragma("unroll") for (int n = 0; n < 2; ++n) _Pragma("unroll") for (int k = 0; k < 2; ++k) \
;         acc[ai][bj][m][n] = mma16_<Epi::BF16>(Bt[n][k], At[m][k], acc[ai][bj][m][n]); __builtin_amdgcn_s_setprio(0); } while (0)
; #define PG8_WAIT_V(n) asm volatile("s_waitcnt vmcnt(" #n ")" ::: "memory")
; #define PG8_WAIT_L(n) asm volatile("s_waitcnt lgkmcnt(" #n ")" ::: "memory")
; #define PG8_BAR __builtin_amdgcn_s_barrier()
; #define PG8_SCHED __builtin_amdgcn_sched_barrier(0)
;     ...
;             PG8_WAIT_V(8); PG8_WAIT_L(0); PG8_BAR; if (!cur.half) { PG8_MMA(1, 0, At, B0); PG8_MMA(1, 1, At, B1); } PG8_BAR; PG8_SCHED;
;             PG8_LDB(B0, 1, 0); PG8_LDB(B1, 1, 1); PG8_SCHED; PG8_LDA(At, 1, 0); PG8_STAGE(PG8_SA(0, 1), a2 + hA, voffA);
;             PG8_WAIT_V(8); PG8_WAIT_L(0); PG8_BAR; PG8_MMA(0, 0, At, B0); PG8_MMA(0, 1, At, B1); PG8_BAR; PG8_SCHED;
;             PG8_LDA(At, 1, 1); PG8_STAGE(PG8_SB(1, 0), b3, voffB); PG8_STAGE(PG8_SB(1, 1), b3 + hB, voffB); PG8_STAGE(PG8_SA(1, 0), a3, voffA);
;             PG8_WAIT_V(8); PG8_WAIT_L(0); PG8_BAR; if (!cur.half) { PG8_MMA(1, 0, At, B0); PG8_MMA(1, 1, At, B1); } PG8_BAR; PG8_SCHED;
	s_setprio 1
	v_mfma_f32_16x16x32_bf16 v[62:65], v[148:151], v[180:183], 0
	v_mfma_f32_16x16x32_bf16 v[58:61], v[156:159], v[180:183], 0
	v_mfma_f32_16x16x32_bf16 v[54:57], v[148:151], v[188:191], 0
	v_mfma_f32_16x16x32_bf16 v[50:53], v[156:159], v[188:191], 0
	v_mfma_f32_16x16x32_bf16 v[38:41], v[148:151], v[214:217], 0
	v_mfma_f32_16x16x32_bf16 v[34:37], v[156:159], v[214:217], 0
	v_mfma_f32_16x16x32_bf16 v[22:25], v[148:151], v[222:225], 0
	v_mfma_f32_16x16x32_bf16 v[18:21], v[156:159], v[222:225], 0
	v_mfma_f32_16x16x32_bf16 v[62:65], v[152:155], v[184:187], v[62:65]
	v_mfma_f32_16x16x32_bf16 v[58:61], v[160:163], v[184:187], v[58:61]
	v_mfma_f32_16x16x32_bf16 v[54:57], v[152:155], v[192:195], v[54:57]
	v_mfma_f32_16x16x32_bf16 v[50:53], v[160:163], v[192:195], v[50:53]
	v_mfma_f32_16x16x32_bf16 v[38:41], v[152:155], v[218:221], v[38:41]
	v_mfma_f32_16x16x32_bf16 v[34:37], v[160:163], v[218:221], v[34:37]
	v_mfma_f32_16x16x32_bf16 v[22:25], v[152:155], v[226:229], v[22:25]
	v_mfma_f32_16x16x32_bf16 v[18:21], v[160:163], v[226:229], v[18:21]
	s_setprio 0
	s_setprio 1
	v_mfma_f32_16x16x32_bf16 v[46:49], v[164:167], v[180:183], 0
	v_mfma_f32_16x16x32_bf16 v[42:45], v[172:175], v[180:183], 0
	v_mfma_f32_16x16x32_bf16 v[30:33], v[164:167], v[188:191], 0
	v_mfma_f32_16x16x32_bf16 v[26:29], v[172:175], v[188:191], 0
	v_mfma_f32_16x16x32_bf16 v[14:17], v[164:167], v[214:217], 0
	v_mfma_f32_16x16x32_bf16 v[10:13], v[172:175], v[214:217], 0
	v_mfma_f32_16x16x32_bf16 v[6:9], v[164:167], v[222:225], 0
	v_mfma_f32_16x16x32_bf16 v[2:5], v[172:175], v[222:225], 0
	v_mfma_f32_16x16x32_bf16 v[46:49], v[168:171], v[184:187], v[46:49]
	v_mfma_f32_16x16x32_bf16 v[42:45], v[176:179], v[184:187], v[42:45]
	v_mfma_f32_16x16x32_bf16 v[30:33], v[168:171], v[192:195], v[30:33]
	v_mfma_f32_16x16x32_bf16 v[26:29], v[176:179], v[192:195], v[26:29]
	v_mfma_f32_16x16x32_bf16 v[14:17], v[168:171], v[218:221], v[14:17]
	v_mfma_f32_16x16x32_bf16 v[10:13], v[176:179], v[218:221], v[10:13]
	v_mfma_f32_16x16x32_bf16 v[6:9], v[168:171], v[226:229], v[6:9]
	v_mfma_f32_16x16x32_bf16 v[2:5], v[176:179], v[226:229], v[2:5]
	s_setprio 0
	s_barrier
	s_add_i32 s50, 0, 0x18000
	s_add_i32 s51, 0, 0x1c000
	v_add_u32_e32 v160, s50, v145
	v_add_u32_e32 v176, s51, v145
	ds_read_b128 v[148:151], v160
	ds_read_b128 v[152:155], v160 offset:1024
	ds_read_b128 v[156:159], v160 offset:2048
	ds_read_b128 v[160:163], v160 offset:3072
	ds_read_b128 v[164:167], v176
	ds_read_b128 v[168:171], v176 offset:1024
	ds_read_b128 v[172:175], v176 offset:2048
	ds_read_b128 v[176:179], v176 offset:3072
	s_add_u32 s30, s30, 0x40000
	s_addc_u32 s31, s31, 0
	s_add_u32 s98, s30, 0xfffc0080
	s_addc_u32 s99, s31, -1
	s_mov_b32 m0, s37
	ds_read_b128 v[180:183], v147 offset:32768
	ds_read_b128 v[184:187], v147 offset:33792
	ds_read_b128 v[188:191], v147 offset:34816
	ds_read_b128 v[192:195], v147 offset:35840
	ds_read_b128 v[214:217], v147 offset:36864
	ds_read_b128 v[218:221], v147 offset:37888
	ds_read_b128 v[222:225], v147 offset:38912
	ds_read_b128 v[226:229], v147 offset:39936
	global_load_lds_dwordx4 v134, s[30:31]
	s_mov_b32 m0, s40
	s_nop 0
	global_load_lds_dwordx4 v132, s[30:31]
	s_waitcnt vmcnt(8) lgkmcnt(0)
	s_barrier
	s_setprio 1
	v_mfma_f32_16x16x32_bf16 v[126:129], v[148:151], v[180:183], v[126:129]
	v_mfma_f32_16x16x32_bf16 v[122:125], v[156:159], v[180:183], v[122:125]
	v_mfma_f32_16x16x32_bf16 v[118:121], v[148:151], v[188:191], v[118:121]
	v_mfma_f32_16x16x32_bf16 v[114:117], v[156:159], v[188:191], v[114:117]
	v_mfma_f32_16x16x32_bf16 v[102:105], v[148:151], v[214:217], v[102:105]
	v_mfma_f32_16x16x32_bf16 v[98:101], v[156:159], v[214:217], v[98:101]
	v_mfma_f32_16x16x32_bf16 v[86:89], v[148:151], v[222:225], v[86:89]
	v_mfma_f32_16x16x32_bf16 v[82:85], v[156:159], v[222:225], v[82:85]
	v_mfma_f32_16x16x32_bf16 v[126:129], v[152:155], v[184:187], v[126:129]
	v_mfma_f32_16x16x32_bf16 v[122:125], v[160:163], v[184:187], v[122:125]
	v_mfma_f32_16x16x32_bf16 v[118:121], v[152:155], v[192:195], v[118:121]
	v_mfma_f32_16x16x32_bf16 v[114:117], v[160:163], v[192:195], v[114:117]
	v_mfma_f32_16x16x32_bf16 v[102:105], v[152:155], v[218:221], v[102:105]
	v_mfma_f32_16x16x32_bf16 v[98:101], v[160:163], v[218:221], v[98:101]
	v_mfma_f32_16x16x32_bf16 v[86:89], v[152:155], v[226:229], v[86:89]
	v_mfma_f32_16x16x32_bf16 v[82:85], v[160:163], v[226:229], v[82:85]
	s_setprio 0
	s_setprio 1
	v_mfma_f32_16x16x32_bf16 v[110:113], v[164:167], v[180:183], v[110:113]
	v_mfma_f32_16x16x32_bf16 v[106:109], v[172:175], v[180:183], v[106:109]
	v_mfma_f32_16x16x32_bf16 v[94:97], v[164:167], v[188:191], v[94:97]
	v_mfma_f32_16x16x32_bf16 v[90:93], v[172:175], v[188:191], v[90:93]
	v_mfma_f32_16x16x32_bf16 v[78:81], v[164:167], v[214:217], v[78:81]
	v_mfma_f32_16x16x32_bf16 v[74:77], v[172:175], v[214:217], v[74:77]
	v_mfma_f32_16x16x32_bf16 v[70:73], v[164:167], v[222:225], v[70:73]
	v_mfma_f32_16x16x32_bf16 v[66:69], v[172:175], v[222:225], v[66:69]
	v_mfma_f32_16x16x32_bf16 v[110:113], v[168:171], v[184:187], v[110:113]
	v_mfma_f32_16x16x32_bf16 v[106:109], v[176:179], v[184:187], v[106:109]
	v_mfma_f32_16x16x32_bf16 v[94:97], v[168:171], v[192:195], v[94:97]
	v_mfma_f32_16x16x32_bf16 v[90:93], v[176:179], v[192:195], v[90:93]
	v_mfma_f32_16x16x32_bf16 v[78:81], v[168:171], v[218:221], v[78:81]
	v_mfma_f32_16x16x32_bf16 v[74:77], v[176:179], v[218:221], v[74:77]
	v_mfma_f32_16x16x32_bf16 v[70:73], v[168:171], v[226:229], v[70:73]
	v_mfma_f32_16x16x32_bf16 v[66:69], v[176:179], v[226:229], v[66:69]
	s_setprio 0
	s_barrier
; #define PG8_STAGE(bufoff, gbase, voff) do { _Pragma("unroll") for (int _i = 0; _i < 2; ++_i) \
;         __builtin_amdgcn_global_load_lds((const unsigned*)((const char*)(gbase) + (voff)[_i]), (LAS unsigned*)(lds + (bufoff) + ldsw + _i * 8192), 16, 0, 0); } while (0)
; #define PG8_LDA(dst, b, h) do { _Pragma("unroll") for (int m = 0; m < 4; ++m) _Pragma("unroll") for (int k = 0; k < 2; ++k) dst[m][k] = *(const LAS f16x8*)(lds + PG8_SA(b, h) + aoff + m * 2048 + k * 1024); } while (0)
; #define PG8_LDB(dst, b, h) do { _Pragma("unroll") for (int n = 0; n < 2; ++n) _Pragma("unroll") for (int k = 0; k < 2; ++k) dst[n][k] = *(const LAS f16x8*)(lds + PG8_SB(b, h) + boff + n * 2048 + k * 1024); } while (0)
; #define PG8_WAIT_V(n) asm volatile("s_waitcnt vmcnt(" #n ")" ::: "memory")
; #define PG8_WAIT_L(n) asm volatile("s_waitcnt lgkmcnt(" #n ")" ::: "memory")
; #define PG8_BAR __builtin_amdgcn_s_barrier()
;     ...
;         for (int t = 0; t < nt; t += 2) {
;             const bool last = (t == nt - 2);
;             const char* a1 = cA + (size_t)(t + 1) * kstep;
;             const char* a2 = last ? nA : cA + (size_t)(t + 2) * kstep; const char* b2 = last ? nB : cB + (size_t)(t + 2) * kstep;
;             const char* a3 = a2 + kstep; const char* b3 = b2 + kstep;
;             if constexpr (SP2) {
;             PG8_LDB(B0, 0, 0); PG8_LDB(B1, 0, 1); PG8_SCHED; PG8_LDA(At, 0, 0); PG8_STAGE(PG8_SA(1, 1), a1 + hA, voffA);
;             PG8_WAIT_V(8); PG8_WAIT_L(0); PG8_BAR; PG8_MMA(0, 0, At, B0); PG8_MMA(0, 1, At, B1); PG8_BAR; PG8_SCHED;
;             PG8_LDA(At, 0, 1); PG8_STAGE(PG8_SB(0, 0), b2, voffB); PG8_STAGE(PG8_SB(0, 1), b2 + hB, voffB); PG8_STAGE(PG8_SA(0, 0), a2, voffA);
;             PG8_WAIT_V(8); PG8_WAIT_L(0); PG8_BAR; if (!cur.half) { PG8_MMA(1, 0, At, B0); PG8_MMA(1, 1, At, B1); } PG8_BAR; PG8_SCHED;
;             PG8_LDB(B0, 1, 0); PG8_LDB(B1, 1, 1); PG8_SCHED; PG8_LDA(At, 1, 0); PG8_STAGE(PG8_SA(0, 1), a2 + hA, voffA);
;             PG8_WAIT_V(8); PG8_WAIT_L(0); PG8_BAR; PG8_MMA(0, 0, At, B0); PG8_MMA(0, 1, At, B1); PG8_BAR; PG8_SCHED;
;             PG8_LDA(At, 1, 1); PG8_STAGE(PG8_SB(1, 0), b3, voffB); PG8_STAGE(PG8_SB(1, 1), b3 + hB, voffB); PG8_STAGE(PG8_SA(1, 0), a3, voffA);
;             PG8_WAIT_V(8); PG8_WAIT_L(0); PG8_BAR; if (!cur.half) { PG8_MMA(1, 0, At, B0); PG8_MMA(1, 1, At, B1); } PG8_BAR; PG8_SCHED;
	s_add_i32 s30, s50, s34
	s_add_u32 s28, s28, 0x80
	s_addc_u32 s29, s29, 0
	s_mov_b32 m0, s30
	ds_read_b128 v[180:183], v147 offset:49152
	ds_read_b128 v[184:187], v147 offset:50176
	ds_read_b128 v[188:191], v147 offset:51200
	ds_read_b128 v[192:195], v147 offset:52224
	ds_read_b128 v[214:217], v147 offset:53248
	ds_read_b128 v[218:221], v147 offset:54272
	ds_read_b128 v[222:225], v147 offset:55296
	ds_read_b128 v[226:229], v147 offset:56320
	global_load_lds_dwordx4 v0, s[28:29]
	s_add_i32 m0, s30, 0x2000
	s_add_i32 s30, s51, s34
	global_load_lds_dwordx4 v130, s[28:29]
	s_add_u32 s28, s28, 0x40000
	s_addc_u32 s29, s29, 0
	s_mov_b32 m0, s30
	s_nop 0
	global_load_lds_dwordx4 v0, s[28:29]
	s_add_i32 m0, s30, 0x2000
	s_nop 0
	global_load_lds_dwordx4 v130, s[28:29]
	s_mov_b32 m0, s41
	s_nop 0
	global_load_lds_dwordx4 v134, s[98:99]
	s_mov_b32 m0, s42
	s_nop 0
	global_load_lds_dwordx4 v132, s[98:99]
	s_waitcnt vmcnt(8) lgkmcnt(0)
	s_barrier
	s_setprio 1
	v_mfma_f32_16x16x32_bf16 v[62:65], v[148:151], v[180:183], v[62:65]
	v_mfma_f32_16x16x32_bf16 v[58:61], v[156:159], v[180:183], v[58:61]
	v_mfma_f32_16x16x32_bf16 v[54:57], v[148:151], v[188:191], v[54:57]
	v_mfma_f32_16x16x32_bf16 v[50:53], v[156:159], v[188:191], v[50:53]
	v_mfma_f32_16x16x32_bf16 v[38:41], v[148:151], v[214:217], v[38:41]
	v_mfma_f32_16x16x32_bf16 v[34:37], v[156:159], v[214:217], v[34:37]
	v_mfma_f32_16x16x32_bf16 v[22:25], v[148:151], v[222:225], v[22:25]
	v_mfma_f32_16x16x32_bf16 v[18:21], v[156:159], v[222:225], v[18:21]
	v_mfma_f32_16x16x32_bf16 v[62:65], v[152:155], v[184:187], v[62:65]
	v_mfma_f32_16x16x32_bf16 v[58:61], v[160:163], v[184:187], v[58:61]
	v_mfma_f32_16x16x32_bf16 v[54:57], v[152:155], v[192:195], v[54:57]
	v_mfma_f32_16x16x32_bf16 v[50:53], v[160:163], v[192:195], v[50:53]
	v_mfma_f32_16x16x32_bf16 v[38:41], v[152:155], v[218:221], v[38:41]
	v_mfma_f32_16x16x32_bf16 v[34:37], v[160:163], v[218:221], v[34:37]
	v_mfma_f32_16x16x32_bf16 v[22:25], v[152:155], v[226:229], v[22:25]
	v_mfma_f32_16x16x32_bf16 v[18:21], v[160:163], v[226:229], v[18:21]
	s_setprio 0
	s_setprio 1
	v_mfma_f32_16x16x32_bf16 v[46:49], v[164:167], v[180:183], v[46:49]
	v_mfma_f32_16x16x32_bf16 v[42:45], v[172:175], v[180:183], v[42:45]
	v_mfma_f32_16x16x32_bf16 v[30:33], v[164:167], v[188:191], v[30:33]
	v_mfma_f32_16x16x32_bf16 v[26:29], v[172:175], v[188:191], v[26:29]
	v_mfma_f32_16x16x32_bf16 v[14:17], v[164:167], v[214:217], v[14:17]
	v_mfma_f32_16x16x32_bf16 v[10:13], v[172:175], v[214:217], v[10:13]
	v_mfma_f32_16x16x32_bf16 v[6:9], v[164:167], v[222:225], v[6:9]
	v_mfma_f32_16x16x32_bf16 v[2:5], v[172:175], v[222:225], v[2:5]
	v_mfma_f32_16x16x32_bf16 v[46:49], v[168:171], v[184:187], v[46:49]
	v_mfma_f32_16x16x32_bf16 v[42:45], v[176:179], v[184:187], v[42:45]
	v_mfma_f32_16x16x32_bf16 v[30:33], v[168:171], v[192:195], v[30:33]
	v_mfma_f32_16x16x32_bf16 v[26:29], v[176:179], v[192:195], v[26:29]
	v_mfma_f32_16x16x32_bf16 v[14:17], v[168:171], v[218:221], v[14:17]
	v_mfma_f32_16x16x32_bf16 v[10:13], v[176:179], v[218:221], v[10:13]
	v_mfma_f32_16x16x32_bf16 v[6:9], v[168:171], v[226:229], v[6:9]
	v_mfma_f32_16x16x32_bf16 v[2:5], v[176:179], v[226:229], v[2:5]
	s_setprio 0
	s_barrier
	s_add_i32 s49, s49, 2
	s_add_u32 s26, s26, 0x100
	s_addc_u32 s27, s27, 0
	s_add_u32 s47, s47, 0x100
	s_addc_u32 s48, s48, 0
	s_cmp_gt_u32 s49, 13

; #define PG8_STAGE(bufoff, gbase, voff) do { _Pragma("unroll") for (int _i = 0; _i < 2; ++_i) \
;         __builtin_amdgcn_global_load_lds((const unsigned*)((const char*)(gbase) + (voff)[_i]), (LAS unsigned*)(lds + (bufoff) + ldsw + _i * 8192), 16, 0, 0); } while (0)
; #define PG8_LDA(dst, b, h) do { _Pragma("unroll") for (int m = 0; m < 4; ++m) _Pragma("unroll") for (int k = 0; k < 2; ++k) dst[m][k] = *(const LAS f16x8*)(lds + PG8_SA(b, h) + aoff + m * 2048 + k * 1024); } while (0)
; #define PG8_LDB(dst, b, h) do { _Pragma("unroll") for (int n = 0; n < 2; ++n) _Pragma("unroll") for (int k = 0; k < 2; ++k) dst[n][k] = *(const LAS f16x8*)(lds + PG8_SB(b, h) + boff + n * 2048 + k * 1024); } while (0)
; #define PG8_MMA(ai, bj, At, Bt) do { __builtin_amdgcn_s_setprio(1); _Pragma("unroll") for (int m = 0; m < 4; ++m) _Pragma("unroll") for (int n = 0; n < 2; ++n) _Pragma("unroll") for (int k = 0; k < 2; ++k) \
;         acc[ai][bj][m][n] = mma16_<Epi::BF16>(Bt[n][k], At[m][k], acc[ai][bj][m][n]); __builtin_amdgcn_s_setprio(0); } while (0)
; #define PG8_WAIT_V(n) asm volatile("s_waitcnt vmcnt(" #n ")" ::: "memory")
; #define PG8_WAIT_L(n) asm volatile("s_waitcnt lgkmcnt(" #n ")" ::: "memory")
;     ...
;     for (;;) {
;         const bool has_next = S.next(ui + 1, nxt);
;         const char* nA = has_next ? (const char*)g.A + (size_t)nxt.pm * tA + (nxt.roff ? hA : (size_t)0) : cA; const char* nB = has_next ? (const char*)g.Bt + (size_t)nxt.pn * tB : cB;
;         for (int t = 0; t < nt; t += 2) {
;             const bool last = (t == nt - 2);
;             const char* a1 = cA + (size_t)(t + 1) * kstep;
;             const char* a2 = last ? nA : cA + (size_t)(t + 2) * kstep; const char* b2 = last ? nB : cB + (size_t)(t + 2) * kstep;
;             const char* a3 = a2 + kstep; const char* b3 = b2 + kstep;
;             if constexpr (SP2) {
;             PG8_LDB(B0, 0, 0); PG8_LDB(B1, 0, 1); PG8_SCHED; PG8_LDA(At, 0, 0); PG8_STAGE(PG8_SA(1, 1), a1 + hA, voffA);
;             PG8_WAIT_V(8); PG8_WAIT_L(0); PG8_BAR; PG8_MMA(0, 0, At, B0); PG8_MMA(0, 1, At, B1); PG8_BAR; PG8_SCHED;
;             PG8_LDA(At, 0, 1); PG8_STAGE(PG8_SB(0, 0), b2, voffB); PG8_STAGE(PG8_SB(0, 1), b2 + hB, voffB); PG8_STAGE(PG8_SA(0, 0), a2, voffA);
;             PG8_WAIT_V(8); PG8_WAIT_L(0); PG8_BAR; if (!cur.half) { PG8_MMA(1, 0, At, B0); PG8_MMA(1, 1, At, B1); } PG8_BAR; PG8_SCHED;
.LBB0_1017:
	s_ashr_i32 s21, s20, 31
	s_lshl_b64 s[2:3], s[20:21], 19
	s_add_u32 s22, s14, s2
	s_addc_u32 s23, s17, s3
	s_and_b64 s[2:3], s[38:39], exec
	s_cselect_b32 s2, s23, s31
	s_cselect_b32 s3, s22, s30
	s_ashr_i32 s19, s18, 31
	s_lshl_b64 s[24:25], s[18:19], 19
	s_add_u32 s24, s12, s24
	s_addc_u32 s25, s13, s25
	s_and_b64 s[36:37], s[38:39], exec
	s_cselect_b32 s19, s25, s35
	s_cselect_b32 s21, s24, s34
	s_add_u32 s30, s30, 0x40080
	s_addc_u32 s31, s31, 0
	s_add_u32 s51, s34, 0x100
	s_addc_u32 s52, s35, 0
	s_mov_b32 s53, -2
	s_add_u32 s34, s30, 0xfffc0080
	s_addc_u32 s35, s31, -1
	s_add_i32 s54, 0, 0x10000
	s_cmp_eq_u32 s53, 12
	s_cselect_b32 s37, s2, s35
	s_cselect_b32 s36, s3, s34
	s_cselect_b32 s35, s19, s52
	s_cselect_b32 s34, s21, s51
	s_add_i32 s56, 0, 0x14000
	v_add_u32_e32 v156, s54, v141
	v_add_u32_e32 v172, s56, v141
	ds_read_b128 v[144:147], v156
	ds_read_b128 v[148:151], v156 offset:1024
	ds_read_b128 v[152:155], v156 offset:2048
	ds_read_b128 v[156:159], v156 offset:3072
	ds_read_b128 v[160:163], v172
	ds_read_b128 v[164:167], v172 offset:1024
	ds_read_b128 v[168:171], v172 offset:2048
	ds_read_b128 v[172:175], v172 offset:3072
	s_add_i32 m0, s27, 0xc000
	ds_read_b128 v[176:179], v143
	ds_read_b128 v[180:183], v143 offset:1024
	ds_read_b128 v[184:187], v143 offset:2048
	ds_read_b128 v[188:191], v143 offset:3072
	ds_read_b128 v[192:195], v143 offset:4096
	ds_read_b128 v[200:203], v143 offset:5120
	ds_read_b128 v[214:217], v143 offset:6144
	ds_read_b128 v[218:221], v143 offset:7168
	global_load_lds_dwordx4 v136, s[30:31]
	s_add_i32 m0, s27, 0xe000
	s_nop 0
	global_load_lds_dwordx4 v138, s[30:31]
	s_waitcnt vmcnt(8) lgkmcnt(0)
	s_barrier
	s_setprio 1
	v_mfma_f32_16x16x32_bf16 v[126:129], v[144:147], v[176:179], 0
	v_mfma_f32_16x16x32_bf16 v[118:121], v[152:155], v[176:179], 0
	v_mfma_f32_16x16x32_bf16 v[110:113], v[144:147], v[184:187], 0
	v_mfma_f32_16x16x32_bf16 v[102:105], v[152:155], v[184:187], 0
	v_mfma_f32_16x16x32_bf16 v[94:97], v[144:147], v[192:195], 0
	v_mfma_f32_16x16x32_bf16 v[86:89], v[152:155], v[192:195], 0
	v_mfma_f32_16x16x32_bf16 v[78:81], v[144:147], v[214:217], 0
	v_mfma_f32_16x16x32_bf16 v[70:73], v[152:155], v[214:217], 0
	v_mfma_f32_16x16x32_bf16 v[126:129], v[148:151], v[180:183], v[126:129]
	v_mfma_f32_16x16x32_bf16 v[118:121], v[156:159], v[180:183], v[118:121]
	v_mfma_f32_16x16x32_bf16 v[110:113], v[148:151], v[188:191], v[110:113]
	v_mfma_f32_16x16x32_bf16 v[102:105], v[156:159], v[188:191], v[102:105]
	v_mfma_f32_16x16x32_bf16 v[94:97], v[148:151], v[200:203], v[94:97]
	v_mfma_f32_16x16x32_bf16 v[86:89], v[156:159], v[200:203], v[86:89]
	v_mfma_f32_16x16x32_bf16 v[78:81], v[148:151], v[218:221], v[78:81]
	v_mfma_f32_16x16x32_bf16 v[70:73], v[156:159], v[218:221], v[70:73]
	s_setprio 0
	s_setprio 1
	v_mfma_f32_16x16x32_bf16 v[122:125], v[160:163], v[176:179], 0
	v_mfma_f32_16x16x32_bf16 v[114:117], v[168:171], v[176:179], 0
	v_mfma_f32_16x16x32_bf16 v[106:109], v[160:163], v[184:187], 0
	v_mfma_f32_16x16x32_bf16 v[98:101], v[168:171], v[184:187], 0
	v_mfma_f32_16x16x32_bf16 v[90:93], v[160:163], v[192:195], 0
	v_mfma_f32_16x16x32_bf16 v[82:85], v[168:171], v[192:195], 0
	v_mfma_f32_16x16x32_bf16 v[74:77], v[160:163], v[214:217], 0
	v_mfma_f32_16x16x32_bf16 v[66:69], v[168:171], v[214:217], 0
	v_mfma_f32_16x16x32_bf16 v[122:125], v[164:167], v[180:183], v[122:125]
	v_mfma_f32_16x16x32_bf16 v[114:117], v[172:175], v[180:183], v[114:117]
	v_mfma_f32_16x16x32_bf16 v[106:109], v[164:167], v[188:191], v[106:109]
	v_mfma_f32_16x16x32_bf16 v[98:101], v[172:175], v[188:191], v[98:101]
	v_mfma_f32_16x16x32_bf16 v[90:93], v[164:167], v[200:203], v[90:93]
	v_mfma_f32_16x16x32_bf16 v[82:85], v[172:175], v[200:203], v[82:85]
	v_mfma_f32_16x16x32_bf16 v[74:77], v[164:167], v[218:221], v[74:77]
	v_mfma_f32_16x16x32_bf16 v[66:69], v[172:175], v[218:221], v[66:69]
	s_setprio 0
	s_barrier
	s_add_i32 s54, s54, s40
	s_mov_b32 m0, s54
	ds_read_b128 v[176:179], v143 offset:16384
	ds_read_b128 v[180:183], v143 offset:17408
	ds_read_b128 v[184:187], v143 offset:18432
	ds_read_b128 v[188:191], v143 offset:19456
	ds_read_b128 v[192:195], v143 offset:20480
	ds_read_b128 v[200:203], v143 offset:21504
	ds_read_b128 v[214:217], v143 offset:22528
	ds_read_b128 v[218:221], v143 offset:23552
	global_load_lds_dwordx4 v0, s[34:35]
	s_add_i32 m0, s54, 0x2000
	s_add_u32 s54, s34, 0x40000
	s_addc_u32 s55, s35, 0
	s_add_i32 s56, s56, s40
	global_load_lds_dwordx4 v130, s[34:35]
	s_mov_b32 m0, s56
	s_nop 0
	global_load_lds_dwordx4 v0, s[54:55]
	s_add_i32 m0, s56, 0x2000
	s_nop 0
	global_load_lds_dwordx4 v130, s[54:55]
	s_mov_b32 m0, s27
	s_nop 0
	global_load_lds_dwordx4 v134, s[36:37]
	s_mov_b32 m0, s29
	s_nop 0
	global_load_lds_dwordx4 v132, s[36:37]
	s_waitcnt vmcnt(8) lgkmcnt(0)
	s_barrier
; #define PG8_STAGE(bufoff, gbase, voff) do { _Pragma("unroll") for (int _i = 0; _i < 2; ++_i) \
;         __builtin_amdgcn_global_load_lds((const unsigned*)((const char*)(gbase) + (voff)[_i]), (LAS unsigned*)(lds + (bufoff) + ldsw + _i * 8192), 16, 0, 0); } while (0)
; #define PG8_LDA(dst, b, h) do { _Pragma("unroll") for (int m = 0; m < 4; ++m) _Pragma("unroll") for (int k = 0; k < 2; ++k) dst[m][k] = *(const LAS f16x8*)(lds + PG8_SA(b, h) + aoff + m * 2048 + k * 1024); } while (0)
; #define PG8_LDB(dst, b, h) do { _Pragma("unroll") for (int n = 0; n < 2; ++n) _Pragma("unroll") for (int k = 0; k < 2; ++k) dst[n][k] = *(const LAS f16x8*)(lds + PG8_SB(b, h) + boff + n * 2048 + k * 1024); } while (0)
; #define PG8_MMA(ai, bj, At, Bt) do { __builtin_amdgcn_s_setprio(1); _Pragma("unroll") for (int m = 0; m < 4; ++m) _Pragma("unroll") for (int n = 0; n < 2; ++n) _Pragma("unroll") for (int k = 0; k < 2; ++k) \
;         acc[ai][bj][m][n] = mma16_<Epi::BF16>(Bt[n][k], At[m][k], acc[ai][bj][m][n]); __builtin_amdgcn_s_setprio(0); } while (0)
; #define PG8_WAIT_V(n) asm volatile("s_waitcnt vmcnt(" #n ")" ::: "memory")
; #define PG8_WAIT_L(n) asm volatile("s_waitcnt lgkmcnt(" #n ")" ::: "memory")
; #define PG8_BAR __builtin_amdgcn_s_barrier()
; #define PG8_SCHED __builtin_amdgcn_sched_barrier(0)
;     ...
;             PG8_WAIT_V(8); PG8_WAIT_L(0); PG8_BAR; if (!cur.half) { PG8_MMA(1, 0, At, B0); PG8_MMA(1, 1, At, B1); } PG8_BAR; PG8_SCHED;
;             PG8_LDB(B0, 1, 0); PG8_LDB(B1, 1, 1); PG8_SCHED; PG8_LDA(At, 1, 0); PG8_STAGE(PG8_SA(0, 1), a2 + hA, voffA);
;             PG8_WAIT_V(8); PG8_WAIT_L(0); PG8_BAR; PG8_MMA(0, 0, At, B0); PG8_MMA(0, 1, At, B1); PG8_BAR; PG8_SCHED;
;             PG8_LDA(At, 1, 1); PG8_STAGE(PG8_SB(1, 0), b3, voffB); PG8_STAGE(PG8_SB(1, 1), b3 + hB, voffB); PG8_STAGE(PG8_SA(1, 0), a3, voffA);
;             PG8_WAIT_V(8); PG8_WAIT_L(0); PG8_BAR; if (!cur.half) { PG8_MMA(1, 0, At, B0); PG8_MMA(1, 1, At, B1); } PG8_BAR; PG8_SCHED;
	s_setprio 1
	v_mfma_f32_16x16x32_bf16 v[62:65], v[144:147], v[176:179], 0
	v_mfma_f32_16x16x32_bf16 v[54:57], v[152:155], v[176:179], 0
	v_mfma_f32_16x16x32_bf16 v[46:49], v[144:147], v[184:187], 0
	v_mfma_f32_16x16x32_bf16 v[38:41], v[152:155], v[184:187], 0
	v_mfma_f32_16x16x32_bf16 v[30:33], v[144:147], v[192:195], 0
	v_mfma_f32_16x16x32_bf16 v[22:25], v[152:155], v[192:195], 0
	v_mfma_f32_16x16x32_bf16 v[14:17], v[144:147], v[214:217], 0
	v_mfma_f32_16x16x32_bf16 v[6:9], v[152:155], v[214:217], 0
	v_mfma_f32_16x16x32_bf16 v[62:65], v[148:151], v[180:183], v[62:65]
	v_mfma_f32_16x16x32_bf16 v[54:57], v[156:159], v[180:183], v[54:57]
	v_mfma_f32_16x16x32_bf16 v[46:49], v[148:151], v[188:191], v[46:49]
	v_mfma_f32_16x16x32_bf16 v[38:41], v[156:159], v[188:191], v[38:41]
	v_mfma_f32_16x16x32_bf16 v[30:33], v[148:151], v[200:203], v[30:33]
	v_mfma_f32_16x16x32_bf16 v[22:25], v[156:159], v[200:203], v[22:25]
	v_mfma_f32_16x16x32_bf16 v[14:17], v[148:151], v[218:221], v[14:17]
	v_mfma_f32_16x16x32_bf16 v[6:9], v[156:159], v[218:221], v[6:9]
	s_setprio 0
	s_setprio 1
	v_mfma_f32_16x16x32_bf16 v[58:61], v[160:163], v[176:179], 0
	v_mfma_f32_16x16x32_bf16 v[50:53], v[168:171], v[176:179], 0
	v_mfma_f32_16x16x32_bf16 v[42:45], v[160:163], v[184:187], 0
	v_mfma_f32_16x16x32_bf16 v[34:37], v[168:171], v[184:187], 0
	v_mfma_f32_16x16x32_bf16 v[26:29], v[160:163], v[192:195], 0
	v_mfma_f32_16x16x32_bf16 v[18:21], v[168:171], v[192:195], 0
	v_mfma_f32_16x16x32_bf16 v[10:13], v[160:163], v[214:217], 0
	v_mfma_f32_16x16x32_bf16 v[2:5], v[168:171], v[214:217], 0
	v_mfma_f32_16x16x32_bf16 v[58:61], v[164:167], v[180:183], v[58:61]
	v_mfma_f32_16x16x32_bf16 v[50:53], v[172:175], v[180:183], v[50:53]
	v_mfma_f32_16x16x32_bf16 v[42:45], v[164:167], v[188:191], v[42:45]
	v_mfma_f32_16x16x32_bf16 v[34:37], v[172:175], v[188:191], v[34:37]
	v_mfma_f32_16x16x32_bf16 v[26:29], v[164:167], v[200:203], v[26:29]
	v_mfma_f32_16x16x32_bf16 v[18:21], v[172:175], v[200:203], v[18:21]
	v_mfma_f32_16x16x32_bf16 v[10:13], v[164:167], v[218:221], v[10:13]
	v_mfma_f32_16x16x32_bf16 v[2:5], v[172:175], v[218:221], v[2:5]
	s_setprio 0
	s_barrier
	s_add_i32 s54, 0, 0x18000
	s_add_i32 s55, 0, 0x1c000
	v_add_u32_e32 v156, s54, v141
	v_add_u32_e32 v172, s55, v141
	ds_read_b128 v[144:147], v156
	ds_read_b128 v[148:151], v156 offset:1024
	ds_read_b128 v[152:155], v156 offset:2048
	ds_read_b128 v[156:159], v156 offset:3072
	ds_read_b128 v[160:163], v172
	ds_read_b128 v[164:167], v172 offset:1024
	ds_read_b128 v[168:171], v172 offset:2048
	ds_read_b128 v[172:175], v172 offset:3072
	s_add_u32 s36, s36, 0x40000
	s_addc_u32 s37, s37, 0
	s_add_u32 s98, s36, 0xfffc0080
	s_addc_u32 s99, s37, -1
	s_mov_b32 m0, s43
	ds_read_b128 v[176:179], v143 offset:32768
	ds_read_b128 v[180:183], v143 offset:33792
	ds_read_b128 v[184:187], v143 offset:34816
	ds_read_b128 v[188:191], v143 offset:35840
	ds_read_b128 v[192:195], v143 offset:36864
	ds_read_b128 v[200:203], v143 offset:37888
	ds_read_b128 v[214:217], v143 offset:38912
	ds_read_b128 v[218:221], v143 offset:39936
	global_load_lds_dwordx4 v134, s[36:37]
	s_mov_b32 m0, s44
	s_nop 0
	global_load_lds_dwordx4 v132, s[36:37]
	s_waitcnt vmcnt(8) lgkmcnt(0)
	s_barrier
	s_setprio 1
	v_mfma_f32_16x16x32_bf16 v[126:129], v[144:147], v[176:179], v[126:129]
	v_mfma_f32_16x16x32_bf16 v[118:121], v[152:155], v[176:179], v[118:121]
	v_mfma_f32_16x16x32_bf16 v[110:113], v[144:147], v[184:187], v[110:113]
	v_mfma_f32_16x16x32_bf16 v[102:105], v[152:155], v[184:187], v[102:105]
	v_mfma_f32_16x16x32_bf16 v[94:97], v[144:147], v[192:195], v[94:97]
	v_mfma_f32_16x16x32_bf16 v[86:89], v[152:155], v[192:195], v[86:89]
	v_mfma_f32_16x16x32_bf16 v[78:81], v[144:147], v[214:217], v[78:81]
	v_mfma_f32_16x16x32_bf16 v[70:73], v[152:155], v[214:217], v[70:73]
	v_mfma_f32_16x16x32_bf16 v[126:129], v[148:151], v[180:183], v[126:129]
	v_mfma_f32_16x16x32_bf16 v[118:121], v[156:159], v[180:183], v[118:121]
	v_mfma_f32_16x16x32_bf16 v[110:113], v[148:151], v[188:191], v[110:113]
	v_mfma_f32_16x16x32_bf16 v[102:105], v[156:159], v[188:191], v[102:105]
	v_mfma_f32_16x16x32_bf16 v[94:97], v[148:151], v[200:203], v[94:97]
	v_mfma_f32_16x16x32_bf16 v[86:89], v[156:159], v[200:203], v[86:89]
	v_mfma_f32_16x16x32_bf16 v[78:81], v[148:151], v[218:221], v[78:81]
	v_mfma_f32_16x16x32_bf16 v[70:73], v[156:159], v[218:221], v[70:73]
	s_setprio 0
	s_setprio 1
	v_mfma_f32_16x16x32_bf16 v[122:125], v[160:163], v[176:179], v[122:125]
	v_mfma_f32_16x16x32_bf16 v[114:117], v[168:171], v[176:179], v[114:117]
	v_mfma_f32_16x16x32_bf16 v[106:109], v[160:163], v[184:187], v[106:109]
	v_mfma_f32_16x16x32_bf16 v[98:101], v[168:171], v[184:187], v[98:101]
	v_mfma_f32_16x16x32_bf16 v[90:93], v[160:163], v[192:195], v[90:93]
	v_mfma_f32_16x16x32_bf16 v[82:85], v[168:171], v[192:195], v[82:85]
	v_mfma_f32_16x16x32_bf16 v[74:77], v[160:163], v[214:217], v[74:77]
	v_mfma_f32_16x16x32_bf16 v[66:69], v[168:171], v[214:217], v[66:69]
	v_mfma_f32_16x16x32_bf16 v[122:125], v[164:167], v[180:183], v[122:125]
	v_mfma_f32_16x16x32_bf16 v[114:117], v[172:175], v[180:183], v[114:117]
	v_mfma_f32_16x16x32_bf16 v[106:109], v[164:167], v[188:191], v[106:109]
	v_mfma_f32_16x16x32_bf16 v[98:101], v[172:175], v[188:191], v[98:101]
	v_mfma_f32_16x16x32_bf16 v[90:93], v[164:167], v[200:203], v[90:93]
	v_mfma_f32_16x16x32_bf16 v[82:85], v[172:175], v[200:203], v[82:85]
	v_mfma_f32_16x16x32_bf16 v[74:77], v[164:167], v[218:221], v[74:77]
	v_mfma_f32_16x16x32_bf16 v[66:69], v[172:175], v[218:221], v[66:69]
	s_setprio 0
	s_barrier
; #define PG8_STAGE(bufoff, gbase, voff) do { _Pragma("unroll") for (int _i = 0; _i < 2; ++_i) \
;         __builtin_amdgcn_global_load_lds((const unsigned*)((const char*)(gbase) + (voff)[_i]), (LAS unsigned*)(lds + (bufoff) + ldsw + _i * 8192), 16, 0, 0); } while (0)
; #define PG8_LDA(dst, b, h) do { _Pragma("unroll") for (int m = 0; m < 4; ++m) _Pragma("unroll") for (int k = 0; k < 2; ++k) dst[m][k] = *(const LAS f16x8*)(lds + PG8_SA(b, h) + aoff + m * 2048 + k * 1024); } while (0)
; #define PG8_MMA(ai, bj, At, Bt) do { __builtin_amdgcn_s_setprio(1); _Pragma("unroll") for (int m = 0; m < 4; ++m) _Pragma("unroll") for (int n = 0; n < 2; ++n) _Pragma("unroll") for (int k = 0; k < 2; ++k) \
;         acc[ai][bj][m][n] = mma16_<Epi::BF16>(Bt[n][k], At[m][k], acc[ai][bj][m][n]); __builtin_amdgcn_s_setprio(0); } while (0)
; #define PG8_WAIT_V(n) asm volatile("s_waitcnt vmcnt(" #n ")" ::: "memory")
; #define PG8_WAIT_L(n) asm volatile("s_waitcnt lgkmcnt(" #n ")" ::: "memory")
; #define PG8_BAR __builtin_amdgcn_s_barrier()
; #define PG8_SCHED __builtin_amdgcn_sched_barrier(0)
;     ...
;             PG8_LDA(At, 1, 1); PG8_STAGE(PG8_SB(1, 0), b3, voffB); PG8_STAGE(PG8_SB(1, 1), b3 + hB, voffB); PG8_STAGE(PG8_SA(1, 0), a3, voffA);
;             PG8_WAIT_V(8); PG8_WAIT_L(0); PG8_BAR; if (!cur.half) { PG8_MMA(1, 0, At, B0); PG8_MMA(1, 1, At, B1); } PG8_BAR; PG8_SCHED;
	s_add_i32 s36, s54, s40
	s_add_u32 s34, s34, 0x80
	s_addc_u32 s35, s35, 0
	s_mov_b32 m0, s36
	ds_read_b128 v[176:179], v143 offset:49152
	ds_read_b128 v[180:183], v143 offset:50176
	ds_read_b128 v[184:187], v143 offset:51200
	ds_read_b128 v[188:191], v143 offset:52224
	ds_read_b128 v[192:195], v143 offset:53248
	ds_read_b128 v[200:203], v143 offset:54272
	ds_read_b128 v[214:217], v143 offset:55296
	ds_read_b128 v[218:221], v143 offset:56320
	global_load_lds_dwordx4 v0, s[34:35]
	s_add_i32 m0, s36, 0x2000
	s_add_i32 s36, s55, s40
	global_load_lds_dwordx4 v130, s[34:35]
	s_add_u32 s34, s34, 0x40000
	s_addc_u32 s35, s35, 0
	s_mov_b32 m0, s36
	s_nop 0
	global_load_lds_dwordx4 v0, s[34:35]
	s_add_i32 m0, s36, 0x2000
	s_nop 0
	global_load_lds_dwordx4 v130, s[34:35]
	s_mov_b32 m0, s45
	s_nop 0
	global_load_lds_dwordx4 v134, s[98:99]
	s_mov_b32 m0, s47
	s_nop 0
	global_load_lds_dwordx4 v132, s[98:99]
	s_waitcnt vmcnt(8) lgkmcnt(0)
	s_barrier
	s_setprio 1
	v_mfma_f32_16x16x32_bf16 v[62:65], v[144:147], v[176:179], v[62:65]
	v_mfma_f32_16x16x32_bf16 v[54:57], v[152:155], v[176:179], v[54:57]
	v_mfma_f32_16x16x32_bf16 v[46:49], v[144:147], v[184:187], v[46:49]
	v_mfma_f32_16x16x32_bf16 v[38:41], v[152:155], v[184:187], v[38:41]
	v_mfma_f32_16x16x32_bf16 v[30:33], v[144:147], v[192:195], v[30:33]
	v_mfma_f32_16x16x32_bf16 v[22:25], v[152:155], v[192:195], v[22:25]
	v_mfma_f32_16x16x32_bf16 v[14:17], v[144:147], v[214:217], v[14:17]
	v_mfma_f32_16x16x32_bf16 v[6:9], v[152:155], v[214:217], v[6:9]
	v_mfma_f32_16x16x32_bf16 v[62:65], v[148:151], v[180:183], v[62:65]
	v_mfma_f32_16x16x32_bf16 v[54:57], v[156:159], v[180:183], v[54:57]
	v_mfma_f32_16x16x32_bf16 v[46:49], v[148:151], v[188:191], v[46:49]
	v_mfma_f32_16x16x32_bf16 v[38:41], v[156:159], v[188:191], v[38:41]
	v_mfma_f32_16x16x32_bf16 v[30:33], v[148:151], v[200:203], v[30:33]
	v_mfma_f32_16x16x32_bf16 v[22:25], v[156:159], v[200:203], v[22:25]
	v_mfma_f32_16x16x32_bf16 v[14:17], v[148:151], v[218:221], v[14:17]
	v_mfma_f32_16x16x32_bf16 v[6:9], v[156:159], v[218:221], v[6:9]
	s_setprio 0
	s_setprio 1
	v_mfma_f32_16x16x32_bf16 v[58:61], v[160:163], v[176:179], v[58:61]
	v_mfma_f32_16x16x32_bf16 v[50:53], v[168:171], v[176:179], v[50:53]
	v_mfma_f32_16x16x32_bf16 v[42:45], v[160:163], v[184:187], v[42:45]
	v_mfma_f32_16x16x32_bf16 v[34:37], v[168:171], v[184:187], v[34:37]
	v_mfma_f32_16x16x32_bf16 v[26:29], v[160:163], v[192:195], v[26:29]
	v_mfma_f32_16x16x32_bf16 v[18:21], v[168:171], v[192:195], v[18:21]
	v_mfma_f32_16x16x32_bf16 v[10:13], v[160:163], v[214:217], v[10:13]
	v_mfma_f32_16x16x32_bf16 v[2:5], v[168:171], v[214:217], v[2:5]
	v_mfma_f32_16x16x32_bf16 v[58:61], v[164:167], v[180:183], v[58:61]
	v_mfma_f32_16x16x32_bf16 v[50:53], v[172:175], v[180:183], v[50:53]
	v_mfma_f32_16x16x32_bf16 v[42:45], v[164:167], v[188:191], v[42:45]
	v_mfma_f32_16x16x32_bf16 v[34:37], v[172:175], v[188:191], v[34:37]
	v_mfma_f32_16x16x32_bf16 v[26:29], v[164:167], v[200:203], v[26:29]
	v_mfma_f32_16x16x32_bf16 v[18:21], v[172:175], v[200:203], v[18:21]
	v_mfma_f32_16x16x32_bf16 v[10:13], v[164:167], v[218:221], v[10:13]
	v_mfma_f32_16x16x32_bf16 v[2:5], v[172:175], v[218:221], v[2:5]
	s_setprio 0
	s_barrier
	s_add_i32 s53, s53, 2
	s_add_u32 s30, s30, 0x100
	s_addc_u32 s31, s31, 0
	s_add_u32 s51, s51, 0x100
	s_addc_u32 s52, s52, 0
	s_cmp_gt_u32 s53, 13
